# RSTD fill loops at GEMM phase start: row-panel index modulo group size (always 8 for these shapes) by s_and instead of the float-reciprocal division chain
# speedup vs baseline: 1.0118x; 1.0034x over previous
;     __device__ __forceinline__ float rstd_global(int row) const { return row_rstd(ssq, row); }
;     __device__ __forceinline__ float rstd_global(int row) const { return row_rstd(ssq, row); }
;     __device__ __forceinline__ float rstd_global(int row) const { return row_rstd(ssq, row); }
;     __host__ __device__ bool next(int i, Unit& u) const {
;         const long L = (long)i * G + c; if (L >= nwg) return false;
;         int wgid = (int)L; { const int q = nwg / NXCD, r = nwg % NXCD, xcd = wgid % NXCD, off = wgid / NXCD; wgid = (xcd < r ? xcd * (q + 1) : r * (q + 1) + (xcd - r) * q) + off; }
;         const int nig = WGM * nN, gid = wgid / nig, fm = gid * WGM, gsz = (nM - fm) < WGM ? (nM - fm) : WGM;
;         u.pm = fm + ((wgid % nig) % gsz); u.pn = (wgid % nig) / gsz; return true;
;     }
; template <class Epi, class Sched, bool ALIGN_EPI = false, bool SP2 = false>
; __device__ __forceinline__ void gemm_phase(PG8_LAS unsigned char* lds, const Gemm g, const Sched& S, const Epi& E) {
;     ...
;         for (int i = 0; S.next(i, tu); ++i) {
;             const int p = tu.pm;
;             if (p != pmc0 && p != pmc1 && p != pmc2 && p != pmc3) {
;                 int slot = -1;
;                 if (pmc0 < 0) { pmc0 = p; slot = 0; } else if (pmc1 < 0) { pmc1 = p; slot = 1; } else if (pmc2 < 0) { pmc2 = p; slot = 2; } else if (pmc3 < 0) { pmc3 = p; slot = 3; }
;                 if (slot >= 0 && tid < 256) rt[slot * 256 + tid] = E.rstd_global(p * 256 + tid);
;             }
;         }
.LBB0_141:
	v_mov_b64_e32 v[2:3], 0x5ff
	v_cmp_gt_i64_e32 vcc, s[12:13], v[2:3]
	s_mov_b32 s49, s4
	s_mov_b32 s7, s11
	s_mov_b32 s30, s10
	s_mov_b32 s27, s3
	s_mov_b64 s[24:25], -1
	s_and_b64 vcc, exec, vcc
	s_cbranch_vccnz .LBB0_140
	s_ashr_i32 s2, s12, 31
	s_lshr_b32 s2, s2, 29
	s_add_i32 s2, s12, s2
	s_ashr_i32 s3, s2, 3
	s_and_b32 s2, s2, -8
	s_sub_i32 s2, s12, s2
	s_cmp_lt_i32 s2, 0
	s_movk_i32 s4, 0xc1
	s_cselect_b32 s4, s4, 0xc0
	s_mul_i32 s2, s2, s4
	s_add_i32 s2, s2, s3
	s_mul_hi_i32 s3, s2, 0x2aaaaaab
	s_lshr_b32 s4, s3, 31
	s_ashr_i32 s3, s3, 4
	s_add_i32 s3, s3, s4
	s_lshl_b32 s4, s3, 3
	s_mulk_i32 s3, 0x60
	s_sub_i32 s2, s2, s3
	s_and_b32 s2, s2, 7
	s_add_i32 s2, s4, s2
	s_cmp_eq_u32 s2, s49
	s_cselect_b64 s[10:11], -1, 0
	s_cmp_eq_u32 s2, s7
	s_cselect_b64 s[18:19], -1, 0
	s_or_b64 s[10:11], s[10:11], s[18:19]
	s_cmp_eq_u32 s2, s30
	s_cselect_b64 s[18:19], -1, 0
	s_or_b64 s[10:11], s[10:11], s[18:19]
	s_cmp_eq_u32 s2, s27
	s_cselect_b64 s[18:19], -1, 0
	s_or_b64 s[10:11], s[10:11], s[18:19]
	s_andn2_b64 vcc, exec, s[10:11]
	s_mov_b32 s4, s49
	s_mov_b32 s11, s7
	s_mov_b32 s10, s30
	s_mov_b32 s3, s27
	s_cbranch_vccz .LBB0_139
	s_cmp_lt_i32 s49, 0
	s_mov_b32 s18, 0
	s_cbranch_scc1 .LBB0_148
	s_cmp_lt_i32 s7, 0
	s_movk_i32 s18, 0x100
	s_cbranch_scc1 .LBB0_149
	s_cmp_lt_i32 s30, 0
	s_movk_i32 s18, 0x200
	s_cbranch_scc1 .LBB0_150
	s_cmp_gt_i32 s27, -1
	s_cbranch_scc0 .LBB0_151
	s_mov_b64 s[24:25], 0
	s_movk_i32 s18, 0xff00
	s_mov_b32 s3, s27
	s_branch .LBB0_152

;     __device__ __forceinline__ float rstd_global(int row) const { return row_rstd(ssq, row); }
;     __device__ __forceinline__ float rstd_global(int row) const { return row_rstd(ssq, row); }
;     __device__ __forceinline__ float rstd_global(int row) const { return row_rstd(ssq, row); }
;     __host__ __device__ bool next(int i, Unit& u) const {
;         const long L = (long)i * G + c; if (L >= nwg) return false;
;         int wgid = (int)L; { const int q = nwg / NXCD, r = nwg % NXCD, xcd = wgid % NXCD, off = wgid / NXCD; wgid = (xcd < r ? xcd * (q + 1) : r * (q + 1) + (xcd - r) * q) + off; }
;         const int nig = WGM * nN, gid = wgid / nig, fm = gid * WGM, gsz = (nM - fm) < WGM ? (nM - fm) : WGM;
;         u.pm = fm + ((wgid % nig) % gsz); u.pn = (wgid % nig) / gsz; return true;
;     }
; template <class Epi, class Sched, bool ALIGN_EPI = false, bool SP2 = false>
; __device__ __forceinline__ void gemm_phase(PG8_LAS unsigned char* lds, const Gemm g, const Sched& S, const Epi& E) {
;     ...
;         for (int i = 0; S.next(i, tu); ++i) {
;             const int p = tu.pm;
;             if (p != pmc0 && p != pmc1 && p != pmc2 && p != pmc3) {
;                 int slot = -1;
;                 if (pmc0 < 0) { pmc0 = p; slot = 0; } else if (pmc1 < 0) { pmc1 = p; slot = 1; } else if (pmc2 < 0) { pmc2 = p; slot = 2; } else if (pmc3 < 0) { pmc3 = p; slot = 3; }
;                 if (slot >= 0 && tid < 256) rt[slot * 256 + tid] = E.rstd_global(p * 256 + tid);
;             }
;         }
.LBB0_230:
	v_mov_b64_e32 v[2:3], 0x5ff
	v_cmp_gt_i64_e32 vcc, s[16:17], v[2:3]
	s_mov_b32 s6, s10
	s_mov_b32 s7, s18
	s_mov_b32 s8, s11
	s_mov_b32 s9, s3
	s_mov_b64 s[24:25], -1
	s_and_b64 vcc, exec, vcc
	s_cbranch_vccnz .LBB0_229
	s_ashr_i32 s2, s16, 31
	s_lshr_b32 s2, s2, 29
	s_add_i32 s2, s16, s2
	s_ashr_i32 s3, s2, 3
	s_and_b32 s2, s2, -8
	s_sub_i32 s2, s16, s2
	s_cmp_lt_i32 s2, 0
	s_movk_i32 s10, 0xc1
	s_cselect_b32 s10, s10, 0xc0
	s_mul_i32 s2, s2, s10
	s_add_i32 s2, s2, s3
	s_mul_hi_i32 s3, s2, 0x2aaaaaab
	s_lshr_b32 s10, s3, 31
	s_ashr_i32 s3, s3, 4
	s_add_i32 s3, s3, s10
	s_lshl_b32 s10, s3, 3
	s_mulk_i32 s3, 0x60
	s_sub_i32 s2, s2, s3
	s_and_b32 s2, s2, 7
	s_add_i32 s2, s10, s2
	s_cmp_eq_u32 s2, s6
	s_cselect_b64 s[10:11], -1, 0
	s_cmp_eq_u32 s2, s7
	s_cselect_b64 s[18:19], -1, 0
	s_or_b64 s[10:11], s[10:11], s[18:19]
	s_cmp_eq_u32 s2, s8
	s_cselect_b64 s[18:19], -1, 0
	s_or_b64 s[10:11], s[10:11], s[18:19]
	s_cmp_eq_u32 s2, s9
	s_cselect_b64 s[18:19], -1, 0
	s_or_b64 s[10:11], s[10:11], s[18:19]
	s_andn2_b64 vcc, exec, s[10:11]
	s_mov_b32 s10, s6
	s_mov_b32 s18, s7
	s_mov_b32 s11, s8
	s_mov_b32 s3, s9
	s_cbranch_vccz .LBB0_228
	s_cmp_lt_i32 s6, 0
	s_mov_b32 s19, 0
	s_cbranch_scc1 .LBB0_237
	s_cmp_lt_i32 s7, 0
	s_movk_i32 s19, 0x100
	s_cbranch_scc1 .LBB0_238
	s_cmp_lt_i32 s8, 0
	s_movk_i32 s19, 0x200
	s_cbranch_scc1 .LBB0_239
	s_cmp_gt_i32 s9, -1
	s_cbranch_scc0 .LBB0_240
	s_mov_b64 s[24:25], 0
	s_movk_i32 s19, 0xff00
	s_mov_b32 s3, s9
	s_branch .LBB0_241

;     __device__ __forceinline__ float rstd_global(int row) const { return row_rstd(ssq, row); }
;     __device__ __forceinline__ float rstd_global(int row) const { return row_rstd(ssq, row); }
;     __device__ __forceinline__ float rstd_global(int row) const { return row_rstd(ssq, row); }
;     __host__ __device__ bool next(int i, Unit& u) const {
;         const long L = (long)i * G + c; if (L >= nwg) return false;
;         int wgid = (int)L; { const int q = nwg / NXCD, r = nwg % NXCD, xcd = wgid % NXCD, off = wgid / NXCD; wgid = (xcd < r ? xcd * (q + 1) : r * (q + 1) + (xcd - r) * q) + off; }
;         const int nig = WGM * nN, gid = wgid / nig, fm = gid * WGM, gsz = (nM - fm) < WGM ? (nM - fm) : WGM;
;         u.pm = fm + ((wgid % nig) % gsz); u.pn = (wgid % nig) / gsz; return true;
;     }
; template <class Epi, class Sched, bool ALIGN_EPI = false, bool SP2 = false>
; __device__ __forceinline__ void gemm_phase(PG8_LAS unsigned char* lds, const Gemm g, const Sched& S, const Epi& E) {
;     ...
;         for (int i = 0; S.next(i, tu); ++i) {
;             const int p = tu.pm;
;             if (p != pmc0 && p != pmc1 && p != pmc2 && p != pmc3) {
;                 int slot = -1;
;                 if (pmc0 < 0) { pmc0 = p; slot = 0; } else if (pmc1 < 0) { pmc1 = p; slot = 1; } else if (pmc2 < 0) { pmc2 = p; slot = 2; } else if (pmc3 < 0) { pmc3 = p; slot = 3; }
;                 if (slot >= 0 && tid < 256) rt[slot * 256 + tid] = E.rstd_global(p * 256 + tid);
;             }
;         }
.LBB0_458:
	v_mov_b64_e32 v[2:3], 0xaff
	v_cmp_gt_i64_e32 vcc, s[16:17], v[2:3]
	s_mov_b32 s4, s9
	s_mov_b32 s6, s11
	s_mov_b32 s7, s10
	s_mov_b32 s8, s3
	s_mov_b64 s[24:25], -1
	s_and_b64 vcc, exec, vcc
	s_cbranch_vccnz .LBB0_457
	s_ashr_i32 s2, s16, 31
	s_lshr_b32 s2, s2, 29
	s_add_i32 s2, s16, s2
	s_ashr_i32 s3, s2, 3
	s_and_b32 s2, s2, -8
	s_sub_i32 s2, s16, s2
	s_cmp_lt_i32 s2, 0
	s_movk_i32 s9, 0x161
	s_cselect_b32 s9, s9, 0x160
	s_mul_i32 s2, s2, s9
	s_add_i32 s2, s2, s3
	s_mul_hi_i32 s3, s2, 0x2e8ba2e9
	s_lshr_b32 s9, s3, 31
	s_ashr_i32 s3, s3, 5
	s_add_i32 s3, s3, s9
	s_lshl_b32 s9, s3, 3
	s_mulk_i32 s3, 0xb0
	s_sub_i32 s2, s2, s3
	s_and_b32 s2, s2, 7
	s_add_i32 s2, s9, s2
	s_cmp_eq_u32 s2, s4
	s_cselect_b64 s[10:11], -1, 0
	s_cmp_eq_u32 s2, s6
	s_cselect_b64 s[18:19], -1, 0
	s_or_b64 s[10:11], s[10:11], s[18:19]
	s_cmp_eq_u32 s2, s7
	s_cselect_b64 s[18:19], -1, 0
	s_or_b64 s[10:11], s[10:11], s[18:19]
	s_cmp_eq_u32 s2, s8
	s_cselect_b64 s[18:19], -1, 0
	s_or_b64 s[10:11], s[10:11], s[18:19]
	s_andn2_b64 vcc, exec, s[10:11]
	s_mov_b32 s9, s4
	s_mov_b32 s11, s6
	s_mov_b32 s10, s7
	s_mov_b32 s3, s8
	s_cbranch_vccz .LBB0_456
	s_cmp_lt_i32 s4, 0
	s_mov_b32 s18, 0
	s_cbranch_scc1 .LBB0_465
	s_cmp_lt_i32 s6, 0
	s_movk_i32 s18, 0x100
	s_cbranch_scc1 .LBB0_466
	s_cmp_lt_i32 s7, 0
	s_movk_i32 s18, 0x200
	s_cbranch_scc1 .LBB0_467
	s_cmp_gt_i32 s8, -1
	s_cbranch_scc0 .LBB0_468
	s_mov_b64 s[24:25], 0
	s_movk_i32 s18, 0xff00
	s_mov_b32 s3, s8
	s_branch .LBB0_469
